# barrier: last XCD leader issues its invalidate before the release atomics and no longer waits for them
# speedup vs baseline: 1.0290x; 1.0024x over previous
.LBB0_86:
	s_andn2_saveexec_b64 s[8:9], s[8:9]
	s_cbranch_execz .LBB0_92
	s_mov_b64 s[12:13], exec
	v_mbcnt_lo_u32_b32 v1, s12, 0
	v_mbcnt_hi_u32_b32 v1, s13, v1
	v_cmp_eq_u32_e32 vcc, 0, v1
	s_and_saveexec_b64 s[10:11], vcc
	s_cbranch_execz .LBB0_89
	s_bcnt1_i32_b64 s12, s[12:13]
	v_mov_b32_e32 v1, 0x4000
	v_mov_b32_e32 v2, s12
	buffer_inv sc1

.LBB0_91:
	s_or_b64 exec, exec, s[10:11]
	s_waitcnt vmcnt(16)
	s_or_b64 exec, exec, s[8:9]
	s_branch .LBB0_93

.LBB0_1117:
	s_andn2_saveexec_b64 s[8:9], s[8:9]
	s_cbranch_execz .LBB0_1123
	s_mov_b64 s[12:13], exec
	v_mbcnt_lo_u32_b32 v0, s12, 0
	v_mbcnt_hi_u32_b32 v0, s13, v0
	v_cmp_eq_u32_e32 vcc, 0, v0
	s_and_saveexec_b64 s[10:11], vcc
	s_cbranch_execz .LBB0_1120
	s_bcnt1_i32_b64 s12, s[12:13]
	v_mov_b32_e32 v0, 0x4000
	v_mov_b32_e32 v1, s12
	buffer_inv sc1
